# rwkv combine: boundary-neighbor loads no longer drain the queue one by one (all loads issued, one wait); layer-start LN/modulate pass restructured like the mid-layer one
# speedup vs baseline: 1.0832x; 1.0159x over previous
; DI float bf2f(u16 v) { return __uint_as_float(((unsigned)v) << 16); }
; __device__ void phase_rwkv_combine(const Params& P, int l, unsigned char* smem, int bid, int nb) {
;     ...
; #pragma unroll
;     for (int i = 0; i < 4; ++i) {
;       const int idx = tid + 256 * i, tok = idx >> 6, r = idx & 63;
;       const int m = m0 + tok;
;       const u16* pp = P.pbuf + (size_t)m * INW + 896 + r;
;       const float pc = bf2f(pp[0]);
;       const float pm = (m - 1 >= seglo) ? bf2f(*(pp - INW)) : 0.f;
;       const float pn = (m + 1 < seghi) ? bf2f(*(pp + INW)) : 0.f;
;       const float ps = pc + mu_g * (0.5f * (pm + pn) - pc);
;       sg[tok * 64 + r] = 1.f / (1.f + expf(-ps));
;     }
.LBB0_267:
	v_mov_b32_e32 v139, 0
	v_mov_b32_e32 v140, 0
	v_mov_b32_e32 v141, 0
	v_mov_b32_e32 v142, 0
	v_mov_b32_e32 v143, 0
	v_mov_b32_e32 v144, 0
	v_mov_b32_e32 v145, 0
	v_mov_b32_e32 v146, 0
	s_mul_hi_i32 s0, s12, 0x38e38e39
	s_lshr_b32 s1, s0, 31
	s_lshr_b32 s0, s0, 5
	s_add_i32 s4, s0, s1
	s_lshl_b32 s13, s12, 4
	s_mulk_i32 s4, 0x900
	s_sub_i32 s0, s13, s4
	s_cmpk_lt_i32 s0, 0x100
	s_cselect_b64 s[0:1], -1, 0
	s_and_b64 s[2:3], s[8:9], s[0:1]
	s_and_b64 vcc, exec, s[2:3]
	s_cbranch_vccnz .LBB0_266
	v_add_u32_e32 v88, s13, v0
	s_movk_i32 s2, 0x1980
	v_mad_i64_i32 v[12:13], s[2:3], v88, s2, v[8:9]
	global_load_ushort v1, v[12:13], off offset:1792
	s_and_b64 s[2:3], s[0:1], exec
	s_cselect_b32 s14, 0, 0x100
	s_add_i32 s14, s14, s4
	s_mov_b64 s[2:3], 0x700
	v_lshl_add_u64 v[12:13], v[12:13], 0, s[2:3]
	v_cmp_lt_i32_e32 vcc, s14, v88
	v_mov_b32_e32 v14, 0
	v_mov_b32_e32 v15, 0
	s_and_saveexec_b64 s[2:3], vcc
	s_cbranch_execz .LBB0_270
	v_add_co_u32_e32 v90, vcc, 0xfffff000, v12
	s_nop 1
	v_addc_co_u32_e32 v91, vcc, -1, v13, vcc
	global_load_ushort v139, v[90:91], off offset:-2432
.LBB0_270:
	s_or_b64 exec, exec, s[2:3]
	s_and_b64 s[0:1], s[0:1], exec
	s_movk_i32 s0, 0x100
	s_cselect_b32 s15, s0, 0x900
	s_add_i32 s15, s15, s4
	v_add_u32_e32 v88, 1, v88
	v_cmp_gt_i32_e32 vcc, s15, v88
	s_and_saveexec_b64 s[0:1], vcc
	s_cbranch_execz .LBB0_272
	v_add_co_u32_e32 v12, vcc, 0x1000, v12
	s_nop 1
	v_addc_co_u32_e32 v13, vcc, 0, v13, vcc
	global_load_ushort v140, v[12:13], off offset:2432
.LBB0_272:
	s_or_b64 exec, exec, s[0:1]
	s_waitcnt vmcnt(0)
	v_lshlrev_b32_e32 v15, 16, v139
	v_lshlrev_b32_e32 v14, 16, v140
	v_lshlrev_b32_e32 v12, 16, v1
	v_add_f32_e32 v1, v15, v14
	v_fma_f32 v1, v1, 0.5, -v12
	v_fmac_f32_e32 v12, v83, v1
	v_mul_f32_e32 v1, 0xbfb8aa3b, v12
	s_mov_b32 s0, 0xbfb8aa3b
	v_fma_f32 v13, v12, s0, -v1
	v_rndne_f32_e32 v14, v1
	v_fmac_f32_e32 v13, 0xb2a5705f, v12
	v_sub_f32_e32 v1, v1, v14
	v_add_f32_e32 v1, v1, v13
	v_exp_f32_e32 v1, v1
	v_cvt_i32_f32_e32 v13, v14
	s_mov_b32 s0, 0x42ce8ed0
	v_cmp_nlt_f32_e32 vcc, s0, v12
	s_mov_b32 s0, 0xc2b17218
	v_ldexp_f32 v13, v1, v13
	v_cndmask_b32_e32 v13, 0, v13, vcc
	v_cmp_ngt_f32_e32 vcc, s0, v12
	v_mov_b32_e32 v1, 0
	s_nop 0
	v_cndmask_b32_e32 v12, v215, v13, vcc
	v_add_f32_e32 v12, 1.0, v12
	v_div_scale_f32 v13, s[0:1], v12, v12, 1.0
	v_rcp_f32_e32 v14, v13
	s_movk_i32 s0, 0x1980
	v_fma_f32 v15, -v13, v14, 1.0
	v_fmac_f32_e32 v14, v15, v14
	v_div_scale_f32 v15, vcc, 1.0, v12, 1.0
	v_mul_f32_e32 v88, v15, v14
	v_fma_f32 v89, -v13, v88, v15
	v_fmac_f32_e32 v88, v89, v14
	v_fma_f32 v13, -v13, v88, v15
	v_add_u32_e32 v15, s13, v85
	v_div_fmas_f32 v13, v13, v14, v88
	v_mad_i64_i32 v[88:89], s[0:1], v15, s0, v[8:9]
	global_load_ushort v14, v[88:89], off offset:1792
	v_div_fixup_f32 v12, v13, v12, 1.0
	s_mov_b64 s[0:1], 0x700
	ds_write_b32 v84, v12
	v_lshl_add_u64 v[12:13], v[88:89], 0, s[0:1]
	v_cmp_lt_i32_e32 vcc, s14, v15
	v_mov_b32_e32 v88, 0
	s_and_saveexec_b64 s[0:1], vcc
	s_cbranch_execz .LBB0_274
	v_add_co_u32_e32 v88, vcc, 0xfffff000, v12
	s_nop 1
	v_addc_co_u32_e32 v89, vcc, -1, v13, vcc
	global_load_ushort v141, v[88:89], off offset:-2432
.LBB0_274:
	s_or_b64 exec, exec, s[0:1]
	v_add_u32_e32 v15, 1, v15
	v_cmp_gt_i32_e32 vcc, s15, v15
	s_and_saveexec_b64 s[0:1], vcc
	s_cbranch_execz .LBB0_276
	v_add_co_u32_e32 v12, vcc, 0x1000, v12
	s_nop 1
	v_addc_co_u32_e32 v13, vcc, 0, v13, vcc
	global_load_ushort v142, v[12:13], off offset:2432
.LBB0_276:
	s_or_b64 exec, exec, s[0:1]
	s_waitcnt vmcnt(0)
	v_lshlrev_b32_e32 v88, 16, v141
	v_lshlrev_b32_e32 v1, 16, v142
	v_lshlrev_b32_e32 v12, 16, v14
	v_add_f32_e32 v1, v88, v1
	v_fma_f32 v1, v1, 0.5, -v12
	v_fmac_f32_e32 v12, v83, v1
	v_mul_f32_e32 v1, 0xbfb8aa3b, v12
	s_mov_b32 s0, 0xbfb8aa3b
	v_fma_f32 v13, v12, s0, -v1
	v_rndne_f32_e32 v14, v1
	v_fmac_f32_e32 v13, 0xb2a5705f, v12
	v_sub_f32_e32 v1, v1, v14
	v_add_f32_e32 v1, v1, v13
	v_exp_f32_e32 v1, v1
	v_cvt_i32_f32_e32 v13, v14
	s_mov_b32 s0, 0x42ce8ed0
	v_cmp_nlt_f32_e32 vcc, s0, v12
	s_mov_b32 s0, 0xc2b17218
	v_ldexp_f32 v13, v1, v13
	v_cndmask_b32_e32 v13, 0, v13, vcc
	v_cmp_ngt_f32_e32 vcc, s0, v12
	v_mov_b32_e32 v1, 0
	s_nop 0
	v_cndmask_b32_e32 v12, v215, v13, vcc
	v_add_f32_e32 v12, 1.0, v12
	v_div_scale_f32 v13, s[0:1], v12, v12, 1.0
	v_rcp_f32_e32 v14, v13
	s_movk_i32 s0, 0x1980
	v_fma_f32 v15, -v13, v14, 1.0
	v_fmac_f32_e32 v14, v15, v14
	v_div_scale_f32 v15, vcc, 1.0, v12, 1.0
	v_mul_f32_e32 v88, v15, v14
	v_fma_f32 v89, -v13, v88, v15
	v_fmac_f32_e32 v88, v89, v14
	v_fma_f32 v13, -v13, v88, v15
	v_add_u32_e32 v15, s13, v86
	v_div_fmas_f32 v13, v13, v14, v88
	v_mad_i64_i32 v[88:89], s[0:1], v15, s0, v[8:9]
	global_load_ushort v14, v[88:89], off offset:1792
	v_div_fixup_f32 v12, v13, v12, 1.0
	s_mov_b64 s[0:1], 0x700
	ds_write_b32 v84, v12 offset:1024
	v_lshl_add_u64 v[12:13], v[88:89], 0, s[0:1]
	v_cmp_lt_i32_e32 vcc, s14, v15
	v_mov_b32_e32 v88, 0
	s_and_saveexec_b64 s[0:1], vcc
	s_cbranch_execz .LBB0_278
	v_add_co_u32_e32 v88, vcc, 0xfffff000, v12
	s_nop 1
	v_addc_co_u32_e32 v89, vcc, -1, v13, vcc
	global_load_ushort v143, v[88:89], off offset:-2432
.LBB0_278:
	s_or_b64 exec, exec, s[0:1]
	v_add_u32_e32 v15, 1, v15
	v_cmp_gt_i32_e32 vcc, s15, v15
	s_and_saveexec_b64 s[0:1], vcc
	s_cbranch_execz .LBB0_280
	v_add_co_u32_e32 v12, vcc, 0x1000, v12
	s_nop 1
	v_addc_co_u32_e32 v13, vcc, 0, v13, vcc
	global_load_ushort v144, v[12:13], off offset:2432
; DI float bf2f(u16 v) { return __uint_as_float(((unsigned)v) << 16); }
; __device__ void phase_rwkv_combine(const Params& P, int l, unsigned char* smem, int bid, int nb) {
;     ...
;       const float pc = bf2f(pp[0]);
;       const float pm = (m - 1 >= seglo) ? bf2f(*(pp - INW)) : 0.f;
;       const float pn = (m + 1 < seghi) ? bf2f(*(pp + INW)) : 0.f;
;       const float ps = pc + mu_g * (0.5f * (pm + pn) - pc);
;       sg[tok * 64 + r] = 1.f / (1.f + expf(-ps));
;     }
;     __syncthreads();
; #pragma unroll 1
;     for (int tq4 = 0; tq4 < 16; tq4 += 4) {
;       float ya[4], yb[4], pcv[4], pmv[4], pnv[4], csa[4], csb[4];
; #pragma unroll
;       for (int u = 0; u < 4; ++u) {
;         const int m = m0 + tq4 + u;
;         ya[u] = bf2f(P.yd[((size_t)m) * 256 + c]); yb[u] = bf2f(P.yd[((size_t)(MALL + m)) * 256 + c]);
;         const u16* pv = P.pbuf + (size_t)m * INW + 512 + c;
;         pcv[u] = bf2f(pv[0]);
;         pmv[u] = (m - 1 >= seglo) ? bf2f(*(pv - INW)) : 0.f;
;         pnv[u] = (m + 1 < seghi) ? bf2f(*(pv + INW)) : 0.f;
;         csa[u] = P.cbuf[((size_t)m) * 4 + wave]; csb[u] = P.cbuf[((size_t)(MALL + m)) * 4 + wave];
;       }
; #pragma unroll
;       for (int u = 0; u < 4; ++u) {
;         const int tok = tq4 + u, m = m0 + tok;
;         float gacc = 0.f;
; #pragma unroll
;         for (int r = 0; r < 64; r += 4) {
;           const float4 s4 = *(const float4*)(sg + tok * 64 + r);
;           gacc += s4.x * gup[r] + s4.y * gup[r + 1] + s4.z * gup[r + 2] + s4.w * gup[r + 3];
;         }
.LBB0_280:
	s_or_b64 exec, exec, s[0:1]
	s_waitcnt vmcnt(0)
	v_lshlrev_b32_e32 v88, 16, v143
	v_lshlrev_b32_e32 v1, 16, v144
	v_lshlrev_b32_e32 v12, 16, v14
	v_add_f32_e32 v1, v88, v1
	v_fma_f32 v1, v1, 0.5, -v12
	v_fmac_f32_e32 v12, v83, v1
	v_mul_f32_e32 v1, 0xbfb8aa3b, v12
	s_mov_b32 s0, 0xbfb8aa3b
	v_fma_f32 v13, v12, s0, -v1
	v_rndne_f32_e32 v14, v1
	v_fmac_f32_e32 v13, 0xb2a5705f, v12
	v_sub_f32_e32 v1, v1, v14
	v_add_f32_e32 v1, v1, v13
	v_exp_f32_e32 v1, v1
	v_cvt_i32_f32_e32 v13, v14
	s_mov_b32 s0, 0x42ce8ed0
	v_cmp_nlt_f32_e32 vcc, s0, v12
	s_mov_b32 s0, 0xc2b17218
	v_ldexp_f32 v13, v1, v13
	v_cndmask_b32_e32 v13, 0, v13, vcc
	v_cmp_ngt_f32_e32 vcc, s0, v12
	v_mov_b32_e32 v1, 0
	s_nop 0
	v_cndmask_b32_e32 v12, v215, v13, vcc
	v_add_f32_e32 v12, 1.0, v12
	v_div_scale_f32 v13, s[0:1], v12, v12, 1.0
	v_rcp_f32_e32 v14, v13
	s_movk_i32 s0, 0x1980
	v_fma_f32 v15, -v13, v14, 1.0
	v_fmac_f32_e32 v14, v15, v14
	v_div_scale_f32 v15, vcc, 1.0, v12, 1.0
	v_mul_f32_e32 v88, v15, v14
	v_fma_f32 v89, -v13, v88, v15
	v_fmac_f32_e32 v88, v89, v14
	v_fma_f32 v13, -v13, v88, v15
	v_add_u32_e32 v15, s13, v87
	v_div_fmas_f32 v13, v13, v14, v88
	v_mad_i64_i32 v[88:89], s[0:1], v15, s0, v[8:9]
	global_load_ushort v14, v[88:89], off offset:1792
	v_div_fixup_f32 v12, v13, v12, 1.0
	s_mov_b64 s[0:1], 0x700
	ds_write_b32 v84, v12 offset:2048
	v_lshl_add_u64 v[12:13], v[88:89], 0, s[0:1]
	v_cmp_lt_i32_e32 vcc, s14, v15
	v_mov_b32_e32 v88, 0
	s_and_saveexec_b64 s[0:1], vcc
	s_cbranch_execz .LBB0_282
	v_add_co_u32_e32 v88, vcc, 0xfffff000, v12
	s_nop 1
	v_addc_co_u32_e32 v89, vcc, -1, v13, vcc
	global_load_ushort v145, v[88:89], off offset:-2432
.LBB0_282:
	s_or_b64 exec, exec, s[0:1]
	v_add_u32_e32 v15, 1, v15
	v_cmp_gt_i32_e32 vcc, s15, v15
	s_and_saveexec_b64 s[0:1], vcc
	s_cbranch_execz .LBB0_284
	v_add_co_u32_e32 v12, vcc, 0x1000, v12
	s_nop 1
	v_addc_co_u32_e32 v13, vcc, 0, v13, vcc
	global_load_ushort v146, v[12:13], off offset:2432
.LBB0_284:
	s_or_b64 exec, exec, s[0:1]
	s_waitcnt vmcnt(0)
	v_lshlrev_b32_e32 v88, 16, v145
	v_lshlrev_b32_e32 v1, 16, v146
	v_lshlrev_b32_e32 v12, 16, v14
	v_add_f32_e32 v1, v88, v1
	v_fma_f32 v1, v1, 0.5, -v12
	v_fmac_f32_e32 v12, v83, v1
	v_mul_f32_e32 v1, 0xbfb8aa3b, v12
	s_mov_b32 s0, 0xbfb8aa3b
	v_fma_f32 v13, v12, s0, -v1
	v_rndne_f32_e32 v14, v1
	v_fmac_f32_e32 v13, 0xb2a5705f, v12
	v_sub_f32_e32 v1, v1, v14
	v_add_f32_e32 v1, v1, v13
	v_exp_f32_e32 v1, v1
	v_cvt_i32_f32_e32 v13, v14
	s_mov_b32 s0, 0x42ce8ed0
	v_cmp_nlt_f32_e32 vcc, s0, v12
	s_mov_b32 s0, 0xc2b17218
	v_ldexp_f32 v1, v1, v13
	v_cndmask_b32_e32 v1, 0, v1, vcc
	v_cmp_ngt_f32_e32 vcc, s0, v12
	s_mov_b32 s16, 0
	s_nop 0
	v_cndmask_b32_e32 v1, v215, v1, vcc
	v_add_f32_e32 v1, 1.0, v1
	v_div_scale_f32 v12, s[0:1], v1, v1, 1.0
	v_rcp_f32_e32 v13, v12
	s_nop 0
	v_fma_f32 v14, -v12, v13, 1.0
	v_fmac_f32_e32 v13, v14, v13
	v_div_scale_f32 v14, vcc, 1.0, v1, 1.0
	v_mul_f32_e32 v15, v14, v13
	v_fma_f32 v88, -v12, v15, v14
	v_fmac_f32_e32 v15, v88, v13
	v_fma_f32 v12, -v12, v15, v14
	v_div_fmas_f32 v12, v12, v13, v15
	v_div_fixup_f32 v1, v12, v1, 1.0
	ds_write_b32 v84, v1 offset:3072
	s_waitcnt lgkmcnt(0)
	s_barrier
	s_branch .LBB0_286
.LBB0_285:
	s_waitcnt vmcnt(0)
	v_lshlrev_b32_e32 v15, 16, v131
	v_lshlrev_b32_e32 v14, 16, v132
	v_lshlrev_b32_e32 v103, 16, v133
	v_lshlrev_b32_e32 v102, 16, v134
	v_lshlrev_b32_e32 v96, 16, v135
	v_lshlrev_b32_e32 v95, 16, v136
	v_lshlrev_b32_e32 v88, 16, v137
	v_lshlrev_b32_e32 v1, 16, v138
	v_lshl_add_u64 v[12:13], s[2:3], 4, v[4:5]
	s_lshl_b32 s2, s16, 8
	s_waitcnt vmcnt(15)
	v_lshlrev_b32_e32 v130, 16, v109
	v_mov_b32_e32 v109, s2
	s_waitcnt vmcnt(2)
	v_lshlrev_b32_e32 v93, 16, v89
	s_waitcnt vmcnt(0)
	v_lshlrev_b32_e32 v89, 16, v100
	v_lshlrev_b32_e32 v100, 16, v92
	v_lshlrev_b32_e32 v92, 16, v112
	v_lshlrev_b32_e32 v126, 16, v106
	v_lshlrev_b32_e32 v127, 16, v110
	v_lshlrev_b32_e32 v106, 16, v111
	ds_read_b128 v[110:113], v109
	v_lshl_add_u64 v[114:115], s[4:5], 4, v[4:5]
	v_lshlrev_b32_e32 v128, 16, v90
	v_lshlrev_b32_e32 v129, 16, v91
	global_load_dword v90, v[12:13], off
	global_load_dword v91, v[114:115], off
	ds_read_b128 v[114:117], v109 offset:16
	ds_read_b128 v[118:121], v109 offset:32
	ds_read_b128 v[122:125], v109 offset:48
	s_waitcnt lgkmcnt(3)
	v_mul_f32_e32 v12, v17, v111
	v_fmac_f32_e32 v12, v16, v110
	s_waitcnt lgkmcnt(2)
	v_mul_f32_e32 v13, v21, v115
	v_fmac_f32_e32 v12, v18, v112
	v_fmac_f32_e32 v13, v20, v114
	v_fmac_f32_e32 v12, v19, v113
	v_fmac_f32_e32 v13, v22, v116
	v_add_f32_e32 v12, 0, v12
	v_fmac_f32_e32 v13, v23, v117
	v_add_f32_e32 v12, v12, v13
	s_waitcnt lgkmcnt(1)
	v_mul_f32_e32 v13, v25, v119
	v_fmac_f32_e32 v13, v24, v118
	v_fmac_f32_e32 v13, v26, v120
	v_fmac_f32_e32 v13, v27, v121
	ds_read_b128 v[110:113], v109 offset:64
	ds_read_b128 v[114:117], v109 offset:80
	v_add_f32_e32 v12, v12, v13
	s_waitcnt lgkmcnt(2)
	v_mul_f32_e32 v13, v29, v123
	v_fmac_f32_e32 v13, v28, v122
	v_fmac_f32_e32 v13, v30, v124
	v_fmac_f32_e32 v13, v31, v125
	v_add_f32_e32 v12, v12, v13
	s_waitcnt lgkmcnt(1)
	v_mul_f32_e32 v13, v33, v111
	v_fmac_f32_e32 v13, v32, v110
	v_fmac_f32_e32 v13, v34, v112
	v_fmac_f32_e32 v13, v35, v113
	ds_read_b128 v[110:113], v109 offset:96
	v_add_f32_e32 v12, v12, v13
	s_waitcnt lgkmcnt(1)
	v_mul_f32_e32 v13, v37, v115
	v_fmac_f32_e32 v13, v36, v114
	v_fmac_f32_e32 v13, v38, v116
	v_fmac_f32_e32 v13, v39, v117
	ds_read_b128 v[114:117], v109 offset:112
	v_add_f32_e32 v12, v12, v13
	s_waitcnt lgkmcnt(1)
	v_mul_f32_e32 v13, v41, v111
	v_fmac_f32_e32 v13, v40, v110
	v_fmac_f32_e32 v13, v42, v112
	v_fmac_f32_e32 v13, v43, v113
	ds_read_b128 v[110:113], v109 offset:128
	v_add_f32_e32 v12, v12, v13
	s_waitcnt lgkmcnt(1)
; __device__ void phase_rwkv_combine(const Params& P, int l, unsigned char* smem, int bid, int nb) {
;     ...
;       for (int u = 0; u < 4; ++u) {
;         const int tok = tq4 + u, m = m0 + tok;
;         float gacc = 0.f;
; #pragma unroll
;         for (int r = 0; r < 64; r += 4) {
;           const float4 s4 = *(const float4*)(sg + tok * 64 + r);
;           gacc += s4.x * gup[r] + s4.y * gup[r + 1] + s4.z * gup[r + 2] + s4.w * gup[r + 3];
;         }
;         const float y = ya[u] + yb[u];
;         const float mean = wave_sum(y) * (1.f / 64.f);
;         const float dd = y - mean;
;         const float var = wave_sum(dd * dd) * (1.f / 64.f);
;         const float yn = dd * rsqrtf(var + 64e-5f) * lng + lnb;
	v_mul_f32_e32 v13, v45, v115
	v_fmac_f32_e32 v13, v44, v114
	v_fmac_f32_e32 v13, v46, v116
	v_fmac_f32_e32 v13, v47, v117
	ds_read_b128 v[114:117], v109 offset:144
	v_add_f32_e32 v12, v12, v13
	s_waitcnt lgkmcnt(1)
	v_mul_f32_e32 v13, v49, v111
	v_fmac_f32_e32 v13, v48, v110
	v_fmac_f32_e32 v13, v50, v112
	v_fmac_f32_e32 v13, v51, v113
	ds_read_b128 v[110:113], v109 offset:160
	v_add_f32_e32 v12, v12, v13
	s_waitcnt lgkmcnt(1)
	v_mul_f32_e32 v13, v53, v115
	v_fmac_f32_e32 v13, v52, v114
	v_fmac_f32_e32 v13, v54, v116
	v_fmac_f32_e32 v13, v55, v117
	ds_read_b128 v[114:117], v109 offset:176
	v_add_f32_e32 v12, v12, v13
	s_waitcnt lgkmcnt(1)
	v_mul_f32_e32 v13, v57, v111
	v_fmac_f32_e32 v13, v56, v110
	v_fmac_f32_e32 v13, v58, v112
	v_fmac_f32_e32 v13, v59, v113
	ds_read_b128 v[110:113], v109 offset:192
	v_add_f32_e32 v12, v12, v13
	s_waitcnt lgkmcnt(1)
	v_mul_f32_e32 v13, v61, v115
	v_fmac_f32_e32 v13, v60, v114
	v_fmac_f32_e32 v13, v62, v116
	v_fmac_f32_e32 v13, v63, v117
	ds_read_b128 v[114:117], v109 offset:208
	v_add_f32_e32 v12, v12, v13
	s_waitcnt lgkmcnt(1)
	v_mul_f32_e32 v13, v65, v111
	v_fmac_f32_e32 v13, v64, v110
	v_fmac_f32_e32 v13, v66, v112
	v_fmac_f32_e32 v13, v67, v113
	ds_read_b128 v[110:113], v109 offset:224
	v_add_f32_e32 v12, v12, v13
	s_waitcnt lgkmcnt(1)
	v_mul_f32_e32 v13, v69, v115
	v_fmac_f32_e32 v13, v68, v114
	v_fmac_f32_e32 v13, v70, v116
	v_fmac_f32_e32 v13, v71, v117
	ds_read_b128 v[114:117], v109 offset:240
	v_add_f32_e32 v12, v12, v13
	s_waitcnt lgkmcnt(1)
	v_mul_f32_e32 v13, v73, v111
	v_fmac_f32_e32 v13, v72, v110
	v_fmac_f32_e32 v13, v74, v112
	v_fmac_f32_e32 v13, v75, v113
	v_add_f32_e32 v12, v12, v13
	s_waitcnt lgkmcnt(0)
	v_mul_f32_e32 v13, v77, v115
	v_fmac_f32_e32 v13, v76, v114
	v_fmac_f32_e32 v13, v78, v116
	v_fmac_f32_e32 v13, v79, v117
	v_add_f32_e32 v125, v128, v129
	v_add_f32_e32 v124, v12, v13
	v_add_f32_e32 v107, v107, v108
	v_add_f32_dpp v12, v125, v125 quad_perm:[1,0,3,2] row_mask:0xf bank_mask:0xf bound_ctrl:1
	v_add_f32_e32 v14, v15, v14
	v_fma_f32 v14, v14, 0.5, -v130
	v_add_f32_dpp v12, v12, v12 quad_perm:[2,3,0,1] row_mask:0xf bank_mask:0xf bound_ctrl:1
	v_fmac_f32_e32 v130, v82, v14
	s_mov_b32 s6, 0x3c800000
	v_add_f32_dpp v12, v12, v12 row_half_mirror row_mask:0xf bank_mask:0xf bound_ctrl:1
	v_lshlrev_b32_e32 v101, 16, v101
	v_lshlrev_b32_e32 v94, 16, v94
	v_add_f32_dpp v12, v12, v12 row_mirror row_mask:0xf bank_mask:0xf bound_ctrl:1
	v_add_f32_e32 v93, v93, v94
	v_readlane_b32 s4, v12, 16
	v_readlane_b32 s5, v12, 48
	v_readlane_b32 s2, v12, 0
	v_readlane_b32 s3, v12, 32
	v_mov_b32_e32 v12, s4
	v_mov_b32_e32 v13, s5
	v_pk_add_f32 v[12:13], s[2:3], v[12:13]
	v_add_f32_dpp v94, v93, v93 quad_perm:[1,0,3,2] row_mask:0xf bank_mask:0xf bound_ctrl:1
	v_add_f32_e32 v12, v12, v13
	v_fmac_f32_e32 v125, 0xbc800000, v12
	v_mul_f32_e32 v12, v125, v125
	v_add_f32_dpp v94, v94, v94 quad_perm:[2,3,0,1] row_mask:0xf bank_mask:0xf bound_ctrl:1
	v_add_f32_e32 v1, v88, v1
	v_mov_b32_dpp v12, v12 quad_perm:[1,0,3,2] row_mask:0xf bank_mask:0xf bound_ctrl:1
	v_fmac_f32_e32 v12, v125, v125
	v_add_f32_dpp v94, v94, v94 row_half_mirror row_mask:0xf bank_mask:0xf bound_ctrl:1
	v_fma_f32 v1, v1, 0.5, -v89
	v_add_f32_dpp v12, v12, v12 quad_perm:[2,3,0,1] row_mask:0xf bank_mask:0xf bound_ctrl:1
	v_add_f32_dpp v94, v94, v94 row_mirror row_mask:0xf bank_mask:0xf bound_ctrl:1
	v_fmac_f32_e32 v89, v82, v1
	v_add_f32_dpp v12, v12, v12 row_half_mirror row_mask:0xf bank_mask:0xf bound_ctrl:1
	s_waitcnt vmcnt(0)
	v_add_f32_e32 v1, v90, v91
	v_add_f32_dpp v12, v12, v12 row_mirror row_mask:0xf bank_mask:0xf bound_ctrl:1
	s_nop 0
	v_readlane_b32 s4, v12, 16
	v_readlane_b32 s5, v12, 48
	v_readlane_b32 s2, v12, 0
	v_readlane_b32 s3, v12, 32
	v_mov_b32_e32 v12, s4
	v_mov_b32_e32 v13, s5
	v_pk_add_f32 v[12:13], s[2:3], v[12:13]
	s_lshl_b64 s[2:3], s[0:1], 11
	s_or_b32 s0, s16, 1
	s_lshl_b32 s1, s0, 8
	v_mov_b32_e32 v128, s1
	ds_read_b128 v[108:111], v128
	ds_read_b128 v[112:115], v128 offset:16
	ds_read_b128 v[116:119], v128 offset:32
	ds_read_b128 v[120:123], v128 offset:48
	v_lshl_add_u64 v[14:15], v[6:7], 0, s[2:3]
	s_mov_b32 s5, 0x800000
	s_or_b32 s0, s0, s13
	s_waitcnt lgkmcnt(3)
	v_mul_f32_e32 v109, v17, v109
	v_fmac_f32_e32 v109, v16, v108
	v_fmac_f32_e32 v109, v18, v110
	v_fmac_f32_e32 v109, v19, v111
	v_add_f32_e32 v108, 0, v109
	s_waitcnt lgkmcnt(2)
	v_mul_f32_e32 v109, v21, v113
	v_fmac_f32_e32 v109, v20, v112
	v_fmac_f32_e32 v109, v22, v114
	v_fmac_f32_e32 v109, v23, v115
	v_add_f32_e32 v108, v108, v109
	s_waitcnt lgkmcnt(1)
	v_mul_f32_e32 v109, v25, v117
	v_fmac_f32_e32 v109, v24, v116
	s_waitcnt lgkmcnt(0)
	v_mul_f32_e32 v113, v29, v121
	v_fmac_f32_e32 v109, v26, v118
	v_fmac_f32_e32 v113, v28, v120
	v_fmac_f32_e32 v109, v27, v119
	v_fmac_f32_e32 v113, v30, v122
	v_add_f32_e32 v112, v108, v109
	ds_read_b128 v[108:111], v128 offset:64
	v_fmac_f32_e32 v113, v31, v123
	v_add_f32_e32 v116, v112, v113
	ds_read_b128 v[112:115], v128 offset:80
	s_waitcnt lgkmcnt(1)
	v_mul_f32_e32 v109, v33, v109
	v_fmac_f32_e32 v109, v32, v108
	v_fmac_f32_e32 v109, v34, v110
	s_waitcnt lgkmcnt(0)
	v_mul_f32_e32 v113, v37, v113
	v_fmac_f32_e32 v113, v36, v112
	v_fmac_f32_e32 v109, v35, v111
	v_fmac_f32_e32 v113, v38, v114
	v_add_f32_e32 v116, v116, v109
	ds_read_b128 v[108:111], v128 offset:96
	v_fmac_f32_e32 v113, v39, v115
	v_add_f32_e32 v116, v116, v113
	ds_read_b128 v[112:115], v128 offset:112
	s_waitcnt lgkmcnt(1)
	v_mul_f32_e32 v109, v41, v109
	v_fmac_f32_e32 v109, v40, v108
	v_fmac_f32_e32 v109, v42, v110
	s_waitcnt lgkmcnt(0)
; DI u16 f2bf(float x) { unsigned u = __float_as_uint(x); u += 0x7fffu + ((u >> 16) & 1u); return (u16)(u >> 16); }
; __device__ void phase_rwkv_combine(const Params& P, int l, unsigned char* smem, int bid, int nb) {
;     ...
;       for (int u = 0; u < 4; ++u) {
;         const int tok = tq4 + u, m = m0 + tok;
;         float gacc = 0.f;
; #pragma unroll
;         for (int r = 0; r < 64; r += 4) {
;           const float4 s4 = *(const float4*)(sg + tok * 64 + r);
;           gacc += s4.x * gup[r] + s4.y * gup[r + 1] + s4.z * gup[r + 2] + s4.w * gup[r + 3];
;         }
;         const float y = ya[u] + yb[u];
;         const float mean = wave_sum(y) * (1.f / 64.f);
;         const float dd = y - mean;
;         const float var = wave_sum(dd * dd) * (1.f / 64.f);
;         const float yn = dd * rsqrtf(var + 64e-5f) * lng + lnb;
;         const float vs = pcv[u] + mu_v * (0.5f * (pmv[u] + pnv[u]) - pcv[u]);
;         P.abuf[(size_t)m * D + c] = f2bf((yn + (csa[u] + csb[u]) * vs) * gacc);
	v_mul_f32_e32 v113, v45, v113
	v_fmac_f32_e32 v113, v44, v112
	v_fmac_f32_e32 v109, v43, v111
	v_fmac_f32_e32 v113, v46, v114
	v_add_f32_e32 v116, v116, v109
	ds_read_b128 v[108:111], v128 offset:128
	v_fmac_f32_e32 v113, v47, v115
	v_add_f32_e32 v116, v116, v113
	ds_read_b128 v[112:115], v128 offset:144
	s_waitcnt lgkmcnt(1)
	v_mul_f32_e32 v109, v49, v109
	v_fmac_f32_e32 v109, v48, v108
	v_fmac_f32_e32 v109, v50, v110
	s_waitcnt lgkmcnt(0)
	v_mul_f32_e32 v113, v53, v113
	v_fmac_f32_e32 v113, v52, v112
	v_fmac_f32_e32 v109, v51, v111
	v_fmac_f32_e32 v113, v54, v114
	v_add_f32_e32 v116, v116, v109
	ds_read_b128 v[108:111], v128 offset:160
	v_fmac_f32_e32 v113, v55, v115
	v_add_f32_e32 v116, v116, v113
	ds_read_b128 v[112:115], v128 offset:176
	s_waitcnt lgkmcnt(1)
	v_mul_f32_e32 v109, v57, v109
	v_fmac_f32_e32 v109, v56, v108
	v_fmac_f32_e32 v109, v58, v110
	s_waitcnt lgkmcnt(0)
	v_mul_f32_e32 v113, v61, v113
	v_fmac_f32_e32 v113, v60, v112
	v_fmac_f32_e32 v109, v59, v111
	v_fmac_f32_e32 v113, v62, v114
	v_add_f32_e32 v116, v116, v109
	ds_read_b128 v[108:111], v128 offset:192
	v_fmac_f32_e32 v113, v63, v115
	v_add_f32_e32 v116, v116, v113
	ds_read_b128 v[112:115], v128 offset:208
	s_waitcnt lgkmcnt(1)
	v_mul_f32_e32 v109, v65, v109
	v_fmac_f32_e32 v109, v64, v108
	v_fmac_f32_e32 v109, v66, v110
	s_waitcnt lgkmcnt(0)
	v_mul_f32_e32 v113, v69, v113
	v_fmac_f32_e32 v113, v68, v112
	v_fmac_f32_e32 v109, v67, v111
	v_fmac_f32_e32 v113, v70, v114
	v_add_f32_e32 v116, v116, v109
	v_fmac_f32_e32 v113, v71, v115
	ds_read_b128 v[108:111], v128 offset:224
	v_add_f32_e32 v116, v116, v113
	ds_read_b128 v[112:115], v128 offset:240
	s_waitcnt lgkmcnt(1)
	v_mul_f32_e32 v109, v73, v109
	v_fmac_f32_e32 v109, v72, v108
	s_waitcnt lgkmcnt(0)
	v_mul_f32_e32 v113, v77, v113
	v_fmac_f32_e32 v113, v76, v112
	v_add_f32_e32 v112, v126, v127
	v_fmac_f32_e32 v109, v74, v110
	v_fmac_f32_e32 v109, v75, v111
	v_add_f32_dpp v108, v112, v112 quad_perm:[1,0,3,2] row_mask:0xf bank_mask:0xf bound_ctrl:1
	v_add_f32_e32 v116, v116, v109
	v_mov_b32_e32 v111, v12
	v_add_f32_dpp v108, v108, v108 quad_perm:[2,3,0,1] row_mask:0xf bank_mask:0xf bound_ctrl:1
	v_fmac_f32_e32 v113, v78, v114
	v_fmac_f32_e32 v113, v79, v115
	v_add_f32_dpp v108, v108, v108 row_half_mirror row_mask:0xf bank_mask:0xf bound_ctrl:1
	s_nop 1
	v_add_f32_dpp v108, v108, v108 row_mirror row_mask:0xf bank_mask:0xf bound_ctrl:1
	s_nop 0
	v_readlane_b32 s1, v108, 16
	v_readlane_b32 s4, v108, 48
	v_readlane_b32 s2, v108, 0
	v_readlane_b32 s3, v108, 32
	v_mov_b32_e32 v108, s1
	v_mov_b32_e32 v109, s4
	v_pk_add_f32 v[108:109], s[2:3], v[108:109]
	s_nop 0
	v_add_f32_e32 v108, v108, v109
	v_fmac_f32_e32 v112, 0xbc800000, v108
	v_mul_f32_e32 v108, v112, v112
	s_nop 1
	v_mov_b32_dpp v108, v108 quad_perm:[1,0,3,2] row_mask:0xf bank_mask:0xf bound_ctrl:1
	v_fmac_f32_e32 v108, v112, v112
	s_nop 1
	v_add_f32_dpp v108, v108, v108 quad_perm:[2,3,0,1] row_mask:0xf bank_mask:0xf bound_ctrl:1
	s_nop 1
	v_add_f32_dpp v108, v108, v108 row_half_mirror row_mask:0xf bank_mask:0xf bound_ctrl:1
	s_nop 1
	v_add_f32_dpp v108, v108, v108 row_mirror row_mask:0xf bank_mask:0xf bound_ctrl:1
	s_nop 0
	v_readlane_b32 s1, v108, 16
	v_readlane_b32 s4, v108, 48
	v_readlane_b32 s2, v108, 0
	v_readlane_b32 s3, v108, 32
	v_mov_b32_e32 v108, s1
	v_mov_b32_e32 v109, s4
	v_pk_add_f32 v[108:109], s[2:3], v[108:109]
	s_mov_b32 s2, 0x3a27c5ac
	v_mov_b32_e32 v110, v108
	v_mov_b32_e32 v12, v109
	v_pk_add_f32 v[108:109], v[110:111], v[12:13]
	v_mov_b64_e32 v[12:13], s[2:3]
	v_pk_fma_f32 v[108:109], v[108:109], s[6:7], v[12:13] op_sel_hi:[1,0,0]
	s_movk_i32 s7, 0x7fff
	v_mul_f32_e32 v110, 0x4b800000, v109
	v_cmp_gt_f32_e32 vcc, s5, v109
	s_ashr_i32 s1, s0, 31
	s_lshl_b64 s[0:1], s[0:1], 11
	v_cndmask_b32_e32 v109, v109, v110, vcc
	v_rsq_f32_e32 v109, v109
	v_add_f32_e32 v110, v116, v113
	v_mul_f32_e32 v111, 0x45800000, v109
	v_cndmask_b32_e32 v109, v109, v111, vcc
	v_mul_f32_e32 v109, v125, v109
	v_fma_f32 v109, v80, v109, v81
	v_fmac_f32_e32 v109, v107, v130
	v_mul_f32_e32 v107, v124, v109
	v_mul_f32_e32 v109, 0x4b800000, v108
	v_cmp_gt_f32_e32 vcc, s5, v108
	s_nop 1
	v_cndmask_b32_e32 v108, v108, v109, vcc
	v_rsq_f32_e32 v108, v108
	v_bfe_u32 v109, v107, 16, 1
	v_add3_u32 v107, v107, v109, s7
	global_store_short_d16_hi v[14:15], v107, off
	v_mul_f32_e32 v14, 0x45800000, v108
	v_cndmask_b32_e32 v14, v108, v14, vcc
	v_add_f32_e32 v15, v103, v102
	v_mul_f32_e32 v14, v112, v14
	v_fma_f32 v15, v15, 0.5, -v106
	v_fma_f32 v14, v80, v14, v81
	v_fmac_f32_e32 v106, v82, v15
	v_add_f32_e32 v15, v104, v105
	v_fmac_f32_e32 v14, v15, v106
	v_mul_f32_e32 v14, v110, v14
	v_bfe_u32 v15, v14, 16, 1
	v_add3_u32 v106, v14, v15, s7
	v_lshl_add_u64 v[14:15], v[6:7], 0, s[0:1]
	s_or_b32 s0, s16, 2
	s_lshl_b32 s1, s0, 8
	v_mov_b32_e32 v118, s1
	ds_read_b128 v[102:105], v118
	global_store_short_d16_hi v[14:15], v106, off
	ds_read_b128 v[106:109], v118 offset:16
	ds_read_b128 v[110:113], v118 offset:32
	ds_read_b128 v[114:117], v118 offset:48
	s_or_b32 s0, s0, s13
	s_waitcnt lgkmcnt(3)
	v_mul_f32_e32 v14, v17, v103
	v_fmac_f32_e32 v14, v16, v102
	s_waitcnt lgkmcnt(2)
	v_mul_f32_e32 v15, v21, v107
	v_fmac_f32_e32 v14, v18, v104
	v_fmac_f32_e32 v15, v20, v106
	v_fmac_f32_e32 v14, v19, v105
	v_fmac_f32_e32 v15, v22, v108
	v_add_f32_e32 v14, 0, v14
	v_fmac_f32_e32 v15, v23, v109
	v_add_f32_e32 v14, v14, v15
	s_waitcnt lgkmcnt(1)
	v_mul_f32_e32 v15, v25, v111
	v_fmac_f32_e32 v15, v24, v110
	v_fmac_f32_e32 v15, v26, v112
	v_fmac_f32_e32 v15, v27, v113
	ds_read_b128 v[102:105], v118 offset:64
	ds_read_b128 v[106:109], v118 offset:80
	v_add_f32_e32 v14, v14, v15
	s_waitcnt lgkmcnt(2)
; DI u16 f2bf(float x) { unsigned u = __float_as_uint(x); u += 0x7fffu + ((u >> 16) & 1u); return (u16)(u >> 16); }
; __device__ void phase_rwkv_combine(const Params& P, int l, unsigned char* smem, int bid, int nb) {
;     ...
;       for (int u = 0; u < 4; ++u) {
;         const int tok = tq4 + u, m = m0 + tok;
;         float gacc = 0.f;
; #pragma unroll
;         for (int r = 0; r < 64; r += 4) {
;           const float4 s4 = *(const float4*)(sg + tok * 64 + r);
;           gacc += s4.x * gup[r] + s4.y * gup[r + 1] + s4.z * gup[r + 2] + s4.w * gup[r + 3];
;         }
;         const float y = ya[u] + yb[u];
;         const float mean = wave_sum(y) * (1.f / 64.f);
;         const float dd = y - mean;
;         const float var = wave_sum(dd * dd) * (1.f / 64.f);
;         const float yn = dd * rsqrtf(var + 64e-5f) * lng + lnb;
;         const float vs = pcv[u] + mu_v * (0.5f * (pmv[u] + pnv[u]) - pcv[u]);
;         P.abuf[(size_t)m * D + c] = f2bf((yn + (csa[u] + csb[u]) * vs) * gacc);
	v_mul_f32_e32 v15, v29, v115
	v_fmac_f32_e32 v15, v28, v114
	v_fmac_f32_e32 v15, v30, v116
	v_fmac_f32_e32 v15, v31, v117
	v_add_f32_e32 v14, v14, v15
	s_waitcnt lgkmcnt(1)
	v_mul_f32_e32 v15, v33, v103
	v_fmac_f32_e32 v15, v32, v102
	v_fmac_f32_e32 v15, v34, v104
	v_fmac_f32_e32 v15, v35, v105
	ds_read_b128 v[102:105], v118 offset:96
	v_add_f32_e32 v14, v14, v15
	s_waitcnt lgkmcnt(1)
	v_mul_f32_e32 v15, v37, v107
	v_fmac_f32_e32 v15, v36, v106
	v_fmac_f32_e32 v15, v38, v108
	v_fmac_f32_e32 v15, v39, v109
	ds_read_b128 v[106:109], v118 offset:112
	v_add_f32_e32 v14, v14, v15
	s_waitcnt lgkmcnt(1)
	v_mul_f32_e32 v15, v41, v103
	v_fmac_f32_e32 v15, v40, v102
	v_fmac_f32_e32 v15, v42, v104
	v_fmac_f32_e32 v15, v43, v105
	ds_read_b128 v[102:105], v118 offset:128
	v_add_f32_e32 v14, v14, v15
	s_waitcnt lgkmcnt(1)
	v_mul_f32_e32 v15, v45, v107
	v_fmac_f32_e32 v15, v44, v106
	v_fmac_f32_e32 v15, v46, v108
	v_fmac_f32_e32 v15, v47, v109
	ds_read_b128 v[106:109], v118 offset:144
	v_add_f32_e32 v14, v14, v15
	s_waitcnt lgkmcnt(1)
	v_mul_f32_e32 v15, v49, v103
	v_fmac_f32_e32 v15, v48, v102
	v_fmac_f32_e32 v15, v50, v104
	v_fmac_f32_e32 v15, v51, v105
	ds_read_b128 v[102:105], v118 offset:160
	v_add_f32_e32 v14, v14, v15
	s_waitcnt lgkmcnt(1)
	v_mul_f32_e32 v15, v53, v107
	v_fmac_f32_e32 v15, v52, v106
	v_fmac_f32_e32 v15, v54, v108
	v_fmac_f32_e32 v15, v55, v109
	ds_read_b128 v[106:109], v118 offset:176
	v_add_f32_e32 v14, v14, v15
	s_waitcnt lgkmcnt(1)
	v_mul_f32_e32 v15, v57, v103
	v_fmac_f32_e32 v15, v56, v102
	v_fmac_f32_e32 v15, v58, v104
	v_fmac_f32_e32 v15, v59, v105
	ds_read_b128 v[102:105], v118 offset:192
	v_add_f32_e32 v14, v14, v15
	s_waitcnt lgkmcnt(1)
	v_mul_f32_e32 v15, v61, v107
	v_fmac_f32_e32 v15, v60, v106
	v_fmac_f32_e32 v15, v62, v108
	v_fmac_f32_e32 v15, v63, v109
	ds_read_b128 v[106:109], v118 offset:208
	v_add_f32_e32 v14, v14, v15
	s_waitcnt lgkmcnt(1)
	v_mul_f32_e32 v15, v65, v103
	v_fmac_f32_e32 v15, v64, v102
	v_fmac_f32_e32 v15, v66, v104
	v_fmac_f32_e32 v15, v67, v105
	ds_read_b128 v[102:105], v118 offset:224
	v_add_f32_e32 v14, v14, v15
	s_waitcnt lgkmcnt(1)
	v_mul_f32_e32 v15, v69, v107
	v_fmac_f32_e32 v15, v68, v106
	v_fmac_f32_e32 v15, v70, v108
	v_fmac_f32_e32 v15, v71, v109
	ds_read_b128 v[106:109], v118 offset:240
	v_add_f32_e32 v14, v14, v15
	s_waitcnt lgkmcnt(1)
	v_mul_f32_e32 v15, v73, v103
	v_fmac_f32_e32 v15, v72, v102
	v_fmac_f32_e32 v15, v74, v104
	v_fmac_f32_e32 v15, v75, v105
	v_add_f32_e32 v14, v14, v15
	s_waitcnt lgkmcnt(0)
	v_mul_f32_e32 v15, v77, v107
	v_fmac_f32_e32 v15, v76, v106
	v_fmac_f32_e32 v15, v78, v108
	v_fmac_f32_e32 v15, v79, v109
	v_add_f32_e32 v117, v100, v101
	v_add_f32_e32 v116, v14, v15
	s_nop 0
	v_add_f32_dpp v14, v117, v117 quad_perm:[1,0,3,2] row_mask:0xf bank_mask:0xf bound_ctrl:1
	s_nop 1
	v_add_f32_dpp v14, v14, v14 quad_perm:[2,3,0,1] row_mask:0xf bank_mask:0xf bound_ctrl:1
	s_nop 1
	v_add_f32_dpp v14, v14, v14 row_half_mirror row_mask:0xf bank_mask:0xf bound_ctrl:1
	s_nop 1
	v_add_f32_dpp v14, v14, v14 row_mirror row_mask:0xf bank_mask:0xf bound_ctrl:1
	s_nop 0
	v_readlane_b32 s1, v14, 16
	v_readlane_b32 s4, v14, 48
	v_readlane_b32 s2, v14, 0
	v_readlane_b32 s3, v14, 32
	v_mov_b32_e32 v14, s1
	v_mov_b32_e32 v15, s4
	v_pk_add_f32 v[14:15], s[2:3], v[14:15]
	s_nop 0
	v_add_f32_e32 v14, v14, v15
	v_fmac_f32_e32 v117, 0xbc800000, v14
	v_mul_f32_e32 v14, v117, v117
	s_nop 1
	v_mov_b32_dpp v14, v14 quad_perm:[1,0,3,2] row_mask:0xf bank_mask:0xf bound_ctrl:1
	v_fmac_f32_e32 v14, v117, v117
	s_nop 1
	v_add_f32_dpp v14, v14, v14 quad_perm:[2,3,0,1] row_mask:0xf bank_mask:0xf bound_ctrl:1
	s_nop 1
	v_add_f32_dpp v14, v14, v14 row_half_mirror row_mask:0xf bank_mask:0xf bound_ctrl:1
	s_nop 1
	v_add_f32_dpp v14, v14, v14 row_mirror row_mask:0xf bank_mask:0xf bound_ctrl:1
	s_nop 0
	v_readlane_b32 s1, v14, 16
	v_readlane_b32 s4, v14, 48
	v_readlane_b32 s2, v14, 0
	v_readlane_b32 s3, v14, 32
	v_mov_b32_e32 v14, s1
	v_mov_b32_e32 v15, s4
	s_ashr_i32 s1, s0, 31
	v_pk_add_f32 v[114:115], s[2:3], v[14:15]
	s_lshl_b64 s[2:3], s[0:1], 11
	s_or_b32 s0, s16, 3
	s_lshl_b32 s1, s0, 8
	v_add_f32_e32 v14, v96, v95
	v_mov_b32_e32 v95, s1
	v_add_f32_e32 v96, v98, v99
	ds_read_b128 v[98:101], v95
	ds_read_b128 v[102:105], v95 offset:16
	ds_read_b128 v[106:109], v95 offset:32
	ds_read_b128 v[110:113], v95 offset:48
	v_fma_f32 v14, v14, 0.5, -v92
	v_readlane_b32 s1, v94, 16
	v_readlane_b32 s4, v94, 48
	s_waitcnt lgkmcnt(3)
	v_mul_f32_e32 v99, v17, v99
	v_fmac_f32_e32 v99, v16, v98
	v_fmac_f32_e32 v99, v18, v100
	v_fmac_f32_e32 v99, v19, v101
	v_add_f32_e32 v98, 0, v99
	s_waitcnt lgkmcnt(2)
	v_mul_f32_e32 v99, v21, v103
	v_fmac_f32_e32 v99, v20, v102
	v_fmac_f32_e32 v99, v22, v104
	v_fmac_f32_e32 v99, v23, v105
	v_add_f32_e32 v98, v98, v99
	s_waitcnt lgkmcnt(1)
	v_mul_f32_e32 v99, v25, v107
	v_fmac_f32_e32 v99, v24, v106
	v_fmac_f32_e32 v99, v26, v108
	v_fmac_f32_e32 v99, v27, v109
	v_add_f32_e32 v102, v98, v99
	ds_read_b128 v[98:101], v95 offset:64
	s_waitcnt lgkmcnt(1)
	v_mul_f32_e32 v103, v29, v111
	v_fmac_f32_e32 v103, v28, v110
	v_fmac_f32_e32 v103, v30, v112
	v_fmac_f32_e32 v103, v31, v113
	v_add_f32_e32 v106, v102, v103
	ds_read_b128 v[102:105], v95 offset:80
	s_waitcnt lgkmcnt(1)
	v_mul_f32_e32 v99, v33, v99
	v_fmac_f32_e32 v99, v32, v98
	v_fmac_f32_e32 v99, v34, v100
	v_fmac_f32_e32 v99, v35, v101
	v_add_f32_e32 v106, v106, v99
	ds_read_b128 v[98:101], v95 offset:96
	s_waitcnt lgkmcnt(1)
	v_mul_f32_e32 v103, v37, v103
	v_fmac_f32_e32 v103, v36, v102
	v_fmac_f32_e32 v103, v38, v104
	v_fmac_f32_e32 v103, v39, v105
	v_add_f32_e32 v106, v106, v103
	ds_read_b128 v[102:105], v95 offset:112
	s_waitcnt lgkmcnt(1)
; DI u16 f2bf(float x) { unsigned u = __float_as_uint(x); u += 0x7fffu + ((u >> 16) & 1u); return (u16)(u >> 16); }
; __device__ void phase_rwkv_combine(const Params& P, int l, unsigned char* smem, int bid, int nb) {
;     ...
;       for (int u = 0; u < 4; ++u) {
;         const int tok = tq4 + u, m = m0 + tok;
;         float gacc = 0.f;
; #pragma unroll
;         for (int r = 0; r < 64; r += 4) {
;           const float4 s4 = *(const float4*)(sg + tok * 64 + r);
;           gacc += s4.x * gup[r] + s4.y * gup[r + 1] + s4.z * gup[r + 2] + s4.w * gup[r + 3];
;         }
;         const float y = ya[u] + yb[u];
;         const float mean = wave_sum(y) * (1.f / 64.f);
;         const float dd = y - mean;
;         const float var = wave_sum(dd * dd) * (1.f / 64.f);
;         const float yn = dd * rsqrtf(var + 64e-5f) * lng + lnb;
;         const float vs = pcv[u] + mu_v * (0.5f * (pmv[u] + pnv[u]) - pcv[u]);
;         P.abuf[(size_t)m * D + c] = f2bf((yn + (csa[u] + csb[u]) * vs) * gacc);
;       }
	v_mul_f32_e32 v99, v41, v99
	v_fmac_f32_e32 v99, v40, v98
	v_fmac_f32_e32 v99, v42, v100
	v_fmac_f32_e32 v99, v43, v101
	v_add_f32_e32 v106, v106, v99
	ds_read_b128 v[98:101], v95 offset:128
	s_waitcnt lgkmcnt(1)
	v_mul_f32_e32 v103, v45, v103
	v_fmac_f32_e32 v103, v44, v102
	v_fmac_f32_e32 v103, v46, v104
	v_fmac_f32_e32 v103, v47, v105
	v_add_f32_e32 v106, v106, v103
	ds_read_b128 v[102:105], v95 offset:144
	s_waitcnt lgkmcnt(1)
	v_mul_f32_e32 v99, v49, v99
	v_fmac_f32_e32 v99, v48, v98
	v_fmac_f32_e32 v99, v50, v100
	v_fmac_f32_e32 v99, v51, v101
	v_add_f32_e32 v106, v106, v99
	ds_read_b128 v[98:101], v95 offset:160
	s_waitcnt lgkmcnt(1)
	v_mul_f32_e32 v103, v53, v103
	v_fmac_f32_e32 v103, v52, v102
	v_fmac_f32_e32 v103, v54, v104
	v_fmac_f32_e32 v103, v55, v105
	v_add_f32_e32 v106, v106, v103
	ds_read_b128 v[102:105], v95 offset:176
	s_waitcnt lgkmcnt(1)
	v_mul_f32_e32 v99, v57, v99
	v_fmac_f32_e32 v99, v56, v98
	v_fmac_f32_e32 v99, v58, v100
	v_fmac_f32_e32 v99, v59, v101
	v_add_f32_e32 v106, v106, v99
	ds_read_b128 v[98:101], v95 offset:192
	s_waitcnt lgkmcnt(1)
	v_mul_f32_e32 v103, v61, v103
	v_fmac_f32_e32 v103, v60, v102
	v_fmac_f32_e32 v103, v62, v104
	v_fmac_f32_e32 v103, v63, v105
	v_add_f32_e32 v106, v106, v103
	ds_read_b128 v[102:105], v95 offset:208
	s_waitcnt lgkmcnt(1)
	v_mul_f32_e32 v99, v65, v99
	v_fmac_f32_e32 v99, v64, v98
	v_fmac_f32_e32 v99, v66, v100
	v_fmac_f32_e32 v99, v67, v101
	v_add_f32_e32 v106, v106, v99
	ds_read_b128 v[98:101], v95 offset:224
	s_waitcnt lgkmcnt(1)
	v_mul_f32_e32 v103, v69, v103
	v_fmac_f32_e32 v103, v68, v102
	v_fmac_f32_e32 v103, v70, v104
	v_fmac_f32_e32 v103, v71, v105
	v_add_f32_e32 v106, v106, v103
	ds_read_b128 v[102:105], v95 offset:240
	s_waitcnt lgkmcnt(1)
	v_mul_f32_e32 v95, v73, v99
	v_fmac_f32_e32 v95, v72, v98
	v_fmac_f32_e32 v95, v74, v100
	v_fmac_f32_e32 v95, v75, v101
	v_fmac_f32_e32 v92, v82, v14
	v_lshl_add_u64 v[14:15], v[6:7], 0, s[2:3]
	v_add_f32_e32 v100, v106, v95
	v_readlane_b32 s2, v94, 0
	v_readlane_b32 s3, v94, 32
	v_mov_b32_e32 v94, s1
	v_mov_b32_e32 v95, s4
	v_pk_add_f32 v[94:95], s[2:3], v[94:95]
	v_mov_b32_e32 v99, v114
	v_add_f32_e32 v94, v94, v95
	v_fmac_f32_e32 v93, 0xbc800000, v94
	v_mul_f32_e32 v94, v93, v93
	s_waitcnt lgkmcnt(0)
	v_mul_f32_e32 v101, v77, v103
	v_fmac_f32_e32 v101, v76, v102
	v_mov_b32_dpp v94, v94 quad_perm:[1,0,3,2] row_mask:0xf bank_mask:0xf bound_ctrl:1
	v_fmac_f32_e32 v94, v93, v93
	v_fmac_f32_e32 v101, v78, v104
	v_fmac_f32_e32 v101, v79, v105
	v_add_f32_dpp v94, v94, v94 quad_perm:[2,3,0,1] row_mask:0xf bank_mask:0xf bound_ctrl:1
	s_or_b32 s0, s0, s13
	s_nop 0
	v_add_f32_dpp v94, v94, v94 row_half_mirror row_mask:0xf bank_mask:0xf bound_ctrl:1
	s_nop 1
	v_add_f32_dpp v94, v94, v94 row_mirror row_mask:0xf bank_mask:0xf bound_ctrl:1
	s_nop 0
	v_readlane_b32 s1, v94, 16
	v_readlane_b32 s4, v94, 48
	v_readlane_b32 s2, v94, 0
	v_readlane_b32 s3, v94, 32
	v_mov_b32_e32 v94, s1
	v_mov_b32_e32 v95, s4
	v_pk_add_f32 v[94:95], s[2:3], v[94:95]
	s_ashr_i32 s1, s0, 31
	v_mov_b32_e32 v98, v94
	v_mov_b32_e32 v114, v95
	v_pk_add_f32 v[94:95], v[98:99], v[114:115]
	s_lshl_b64 s[0:1], s[0:1], 11
	v_pk_fma_f32 v[12:13], v[94:95], s[6:7], v[12:13] op_sel_hi:[1,0,0]
	s_nop 0
	v_mul_f32_e32 v94, 0x4b800000, v13
	v_cmp_gt_f32_e32 vcc, s5, v13
	s_nop 1
	v_cndmask_b32_e32 v13, v13, v94, vcc
	v_rsq_f32_e32 v13, v13
	v_add_f32_e32 v94, v100, v101
	v_mul_f32_e32 v95, 0x45800000, v13
	v_cndmask_b32_e32 v13, v13, v95, vcc
	v_mul_f32_e32 v13, v117, v13
	v_fma_f32 v13, v80, v13, v81
	v_fmac_f32_e32 v13, v96, v92
	v_mul_f32_e32 v92, 0x4b800000, v12
	v_cmp_gt_f32_e32 vcc, s5, v12
	v_mul_f32_e32 v13, v116, v13
	s_nop 0
	v_cndmask_b32_e32 v12, v12, v92, vcc
	v_rsq_f32_e32 v12, v12
	v_bfe_u32 v92, v13, 16, 1
	v_add3_u32 v13, v13, v92, s7
	global_store_short_d16_hi v[14:15], v13, off
	v_mul_f32_e32 v13, 0x45800000, v12
	v_cndmask_b32_e32 v12, v12, v13, vcc
	v_mul_f32_e32 v12, v93, v12
	v_fma_f32 v12, v80, v12, v81
	v_fmac_f32_e32 v12, v1, v89
	v_mul_f32_e32 v1, v94, v12
	v_bfe_u32 v12, v1, 16, 1
	v_add3_u32 v1, v1, v12, s7
	v_lshl_add_u64 v[12:13], v[6:7], 0, s[0:1]
	s_add_i32 s0, s16, 4
	s_cmp_gt_u32 s16, 11
	s_mov_b32 s16, s0
	global_store_short_d16_hi v[12:13], v1, off
	s_cbranch_scc1 .LBB0_265
; DI float bf2f(u16 v) { return __uint_as_float(((unsigned)v) << 16); }
; __device__ void phase_rwkv_combine(const Params& P, int l, unsigned char* smem, int bid, int nb) {
;     ...
;     for (int tq4 = 0; tq4 < 16; tq4 += 4) {
;       float ya[4], yb[4], pcv[4], pmv[4], pnv[4], csa[4], csb[4];
; #pragma unroll
;       for (int u = 0; u < 4; ++u) {
;         const int m = m0 + tq4 + u;
;         ya[u] = bf2f(P.yd[((size_t)m) * 256 + c]); yb[u] = bf2f(P.yd[((size_t)(MALL + m)) * 256 + c]);
;         const u16* pv = P.pbuf + (size_t)m * INW + 512 + c;
;         pcv[u] = bf2f(pv[0]);
;         pmv[u] = (m - 1 >= seglo) ? bf2f(*(pv - INW)) : 0.f;
;         pnv[u] = (m + 1 < seghi) ? bf2f(*(pv + INW)) : 0.f;
;         csa[u] = P.cbuf[((size_t)m) * 4 + wave]; csb[u] = P.cbuf[((size_t)(MALL + m)) * 4 + wave];
;       }
.LBB0_286:
	v_mov_b32_e32 v131, 0
	v_mov_b32_e32 v132, 0
	v_mov_b32_e32 v133, 0
	v_mov_b32_e32 v134, 0
	v_mov_b32_e32 v135, 0
	v_mov_b32_e32 v136, 0
	v_mov_b32_e32 v137, 0
	v_mov_b32_e32 v138, 0
	s_or_b32 s0, s16, s13
	s_ashr_i32 s1, s0, 31
	s_add_i32 s4, s0, 0x9000
	s_lshl_b64 s[2:3], s[0:1], 9
	s_ashr_i32 s5, s4, 31
	v_lshl_add_u64 v[12:13], v[2:3], 0, s[2:3]
	s_lshl_b64 s[2:3], s[4:5], 9
	v_lshl_add_u64 v[14:15], v[2:3], 0, s[2:3]
	global_load_ushort v90, v[12:13], off
	global_load_ushort v91, v[14:15], off
	v_mad_i64_i32 v[12:13], s[2:3], s0, v216, v[10:11]
	global_load_ushort v109, v[12:13], off offset:1024
	s_mov_b64 s[2:3], 0x400
	v_lshl_add_u64 v[12:13], v[12:13], 0, s[2:3]
	v_mov_b32_e32 v14, 0
	s_cmp_le_i32 s0, s14
	v_mov_b32_e32 v15, 0
	s_cbranch_scc1 .LBB0_288
	v_add_co_u32_e32 v88, vcc, 0xfffff000, v12
	s_nop 1
	v_addc_co_u32_e32 v89, vcc, -1, v13, vcc
	global_load_ushort v131, v[88:89], off offset:-2432
.LBB0_288:
	s_or_b32 s2, s0, 1
	s_cmp_ge_i32 s2, s15
	s_cbranch_scc1 .LBB0_290
	v_add_co_u32_e32 v12, vcc, 0x1000, v12
	s_nop 1
	v_addc_co_u32_e32 v13, vcc, 0, v13, vcc
	global_load_ushort v132, v[12:13], off offset:2432
.LBB0_290:
	s_ashr_i32 s3, s2, 31
	s_add_i32 s10, s0, 0x9001
	v_lshl_add_u64 v[12:13], s[0:1], 4, v[4:5]
	v_lshl_add_u64 v[88:89], s[4:5], 4, v[4:5]
	s_lshl_b64 s[4:5], s[2:3], 9
	s_ashr_i32 s11, s10, 31
	global_load_dword v107, v[12:13], off
	global_load_dword v108, v[88:89], off
	v_lshl_add_u64 v[12:13], v[2:3], 0, s[4:5]
	s_lshl_b64 s[4:5], s[10:11], 9
	v_lshl_add_u64 v[88:89], v[2:3], 0, s[4:5]
	global_load_ushort v106, v[12:13], off
	global_load_ushort v110, v[88:89], off
	v_mad_i64_i32 v[12:13], s[4:5], s2, v216, v[10:11]
	global_load_ushort v111, v[12:13], off offset:1024
	s_mov_b64 s[4:5], 0x400
	s_cmp_ge_i32 s0, s14
	v_lshl_add_u64 v[12:13], v[12:13], 0, s[4:5]
	v_mov_b32_e32 v102, 0
	s_cselect_b64 s[6:7], -1, 0
	s_cmp_lt_i32 s0, s14
	v_mov_b32_e32 v103, 0
	s_cbranch_scc1 .LBB0_292
	v_add_co_u32_e32 v88, vcc, 0xfffff000, v12
	s_nop 1
	v_addc_co_u32_e32 v89, vcc, -1, v13, vcc
	global_load_ushort v133, v[88:89], off offset:-2432
.LBB0_292:
	s_or_b32 s4, s0, 2
	s_cmp_ge_i32 s4, s15
	s_cbranch_scc1 .LBB0_294
	v_add_co_u32_e32 v12, vcc, 0x1000, v12
	s_nop 1
	v_addc_co_u32_e32 v13, vcc, 0, v13, vcc
	global_load_ushort v134, v[12:13], off offset:2432
.LBB0_294:
	v_lshl_add_u64 v[88:89], s[10:11], 4, v[4:5]
	s_ashr_i32 s5, s4, 31
	s_add_i32 s10, s0, 0x9002
	v_lshl_add_u64 v[12:13], s[2:3], 4, v[4:5]
	s_lshl_b64 s[2:3], s[4:5], 9
	s_ashr_i32 s11, s10, 31
	global_load_dword v104, v[12:13], off
	global_load_dword v105, v[88:89], off
	v_lshl_add_u64 v[12:13], v[2:3], 0, s[2:3]
	s_lshl_b64 s[2:3], s[10:11], 9
	v_lshl_add_u64 v[88:89], v[2:3], 0, s[2:3]
	global_load_ushort v92, v[12:13], off
	global_load_ushort v101, v[88:89], off
	v_mad_i64_i32 v[12:13], s[2:3], s4, v216, v[10:11]
	global_load_ushort v112, v[12:13], off offset:1024
	s_mov_b64 s[2:3], 0x400
	v_lshl_add_u64 v[12:13], v[12:13], 0, s[2:3]
	v_mov_b32_e32 v95, 0
	s_andn2_b64 vcc, exec, s[6:7]
	v_mov_b32_e32 v96, 0
	s_cbranch_vccnz .LBB0_296
	v_add_co_u32_e32 v88, vcc, 0xfffff000, v12
	s_nop 1
	v_addc_co_u32_e32 v89, vcc, -1, v13, vcc
	global_load_ushort v135, v[88:89], off offset:-2432
.LBB0_296:
	s_or_b32 s2, s0, 3
	s_cmp_ge_i32 s2, s15
	s_cbranch_scc1 .LBB0_298
	v_add_co_u32_e32 v12, vcc, 0x1000, v12
	s_nop 1
	v_addc_co_u32_e32 v13, vcc, 0, v13, vcc
	global_load_ushort v136, v[12:13], off offset:2432
.LBB0_298:
	s_ashr_i32 s3, s2, 31
	v_lshl_add_u64 v[12:13], s[4:5], 4, v[4:5]
	s_lshl_b64 s[4:5], s[2:3], 9
	v_lshl_add_u64 v[88:89], s[10:11], 4, v[4:5]
	global_load_dword v98, v[12:13], off
	global_load_dword v99, v[88:89], off
	v_lshl_add_u64 v[12:13], v[2:3], 0, s[4:5]
	s_add_i32 s4, s0, 0x9003
	s_ashr_i32 s5, s4, 31
	s_lshl_b64 s[6:7], s[4:5], 9
	v_lshl_add_u64 v[114:115], v[2:3], 0, s[6:7]
	global_load_ushort v89, v[12:13], off
	global_load_ushort v94, v[114:115], off
	v_mad_i64_i32 v[12:13], s[6:7], s2, v216, v[10:11]
	global_load_ushort v100, v[12:13], off offset:1024
	s_mov_b64 s[6:7], 0x400
	v_lshl_add_u64 v[12:13], v[12:13], 0, s[6:7]
	v_mov_b32_e32 v1, 0
	s_cmp_le_i32 s2, s14
	v_mov_b32_e32 v88, 0
	s_cbranch_scc1 .LBB0_300
	v_add_co_u32_e32 v114, vcc, 0xfffff000, v12
	s_nop 1
	v_addc_co_u32_e32 v115, vcc, -1, v13, vcc
	global_load_ushort v137, v[114:115], off offset:-2432
.LBB0_300:
	s_add_i32 s6, s0, 4
	s_cmp_ge_i32 s6, s15
	s_cbranch_scc1 .LBB0_285
	v_add_co_u32_e32 v12, vcc, 0x1000, v12
	s_nop 1
	v_addc_co_u32_e32 v13, vcc, 0, v13, vcc
	global_load_ushort v138, v[12:13], off offset:2432
	s_branch .LBB0_285

;     ...
;   const int mstep = nb * 4;
;   int mn = bid * 4 + wave;
;   while (mn < MALL && latent_only && (mn % TALL) < CTX) mn += mstep;
;   float4 nv0 = make_float4(0.f, 0.f, 0.f, 0.f), nv1 = nv0, nv2 = nv0, nv3 = nv0;
;   if (mn < MALL) {
;     const int b = mn / TALL, t = mn - b * TALL; const bool isctx = t < CTX;
;     const float* src = do_ln ? (isctx ? P.zctx + ((size_t)(b * CTX + t)) * D : P.out + ((size_t)(b * SEQ + t - CTX)) * D)
;                              : (isctx ? P.ctx + ((size_t)(b * CTX + t)) * D : P.x + ((size_t)(b * SEQ + t - CTX)) * D);
;     { typedef float f32x4n __attribute__((ext_vector_type(4))); const f32x4n t0 = __builtin_nontemporal_load((const f32x4n*)(src + lane * 4)), t1 = __builtin_nontemporal_load((const f32x4n*)(src + 256 + lane * 4)), t2 = __builtin_nontemporal_load((const f32x4n*)(src + 512 + lane * 4)), t3 = __builtin_nontemporal_load((const f32x4n*)(src + 768 + lane * 4)); nv0 = make_float4(t0[0], t0[1], t0[2], t0[3]); nv1 = make_float4(t1[0], t1[1], t1[2], t1[3]); nv2 = make_float4(t2[0], t2[1], t2[2], t2[3]); nv3 = make_float4(t3[0], t3[1], t3[2], t3[3]); }
;   }
.LBB0_611:
	v_and_b32_e32 v18, 63, v1
	v_ashrrev_i32_e32 v1, 31, v0
	v_lshlrev_b64 v[0:1], 12, v[0:1]
	v_lshl_add_u64 v[0:1], v[2:3], 0, v[0:1]
	v_lshlrev_b32_e32 v96, 4, v18
	v_lshl_add_u64 v[8:9], v[0:1], 0, v[96:97]
	global_load_dwordx4 v[0:3], v[8:9], off offset:3072 nt
	global_load_dwordx4 v[4:7], v[8:9], off offset:2048 nt
	global_load_dwordx4 v[12:15], v[8:9], off offset:1024 nt
	s_nop 0
	global_load_dwordx4 v[8:11], v[8:9], off nt
	v_readlane_b32 s4, v251, 50
	v_readlane_b32 s6, v251, 25
	v_readlane_b32 s5, v251, 51
	v_readlane_b32 s7, v251, 26
	s_mov_b32 s28, s4
	s_lshl_b32 s4, s4, 10
	s_mov_b32 s5, s7
	s_add_i32 s6, s4, 0xfffffc00
	v_writelane_b32 v251, s4, 25
	v_readlane_b32 s12, v253, 0
	v_readlane_b32 s18, v253, 6
	v_writelane_b32 v251, s5, 26
	s_lshl_b64 s[4:5], s[6:7], 2
	v_readlane_b32 s19, v253, 7
	s_add_u32 s8, s18, s4
	v_readlane_b32 s20, v253, 8
	s_addc_u32 s9, s19, s5
	v_readlane_b32 s21, v253, 9
	s_add_u32 s4, s20, s4
	s_addc_u32 s5, s21, s5
	v_readlane_b32 s6, v252, 25
	v_readlane_b32 s13, v253, 1
	s_cmp_gt_i32 s6, 9
	s_cselect_b32 s7, s5, s13
	s_cselect_b32 s6, s4, s12
	s_waitcnt vmcnt(4)
	v_lshl_add_u64 v[36:37], s[6:7], 0, v[96:97]
	v_readlane_b32 s6, v251, 23
	v_ashrrev_i32_e32 v17, 31, v16
	v_readlane_b32 s7, v251, 24
	v_readlane_b32 s14, v253, 2
	v_readlane_b32 s15, v253, 3
	v_readlane_b32 s16, v253, 4
	v_readlane_b32 s17, v253, 5
	v_readlane_b32 s22, v253, 10
	v_readlane_b32 s23, v253, 11
	v_readlane_b32 s24, v253, 12
	v_readlane_b32 s25, v253, 13
	v_readlane_b32 s26, v253, 14
	v_readlane_b32 s27, v253, 15
	v_lshl_add_u64 v[16:17], s[6:7], 0, v[16:17]
	v_readlane_b32 s6, v251, 21
	v_readlane_b32 s12, v253, 52
	v_readlane_b32 s7, v251, 22
	v_readlane_b32 s26, v252, 2
	v_readlane_b32 s27, v252, 3
	v_lshl_add_u64 v[38:39], v[16:17], 3, s[6:7]
	v_lshlrev_b64 v[16:17], 11, v[16:17]
	v_readlane_b32 s13, v253, 53
	v_readlane_b32 s14, v253, 54
	s_cselect_b32 s9, s9, s27
	s_cselect_b32 s8, s8, s26
	v_lshl_or_b32 v16, v18, 3, v16
	v_lshlrev_b32_e32 v32, 2, v18
	v_cmp_eq_u32_e64 s[4:5], 0, v18
	v_lshl_add_u64 v[34:35], s[8:9], 0, v[96:97]
	s_mul_i32 s14, s28, 17
	v_lshl_add_u64 v[40:41], s[66:67], 0, v[16:17]
	s_mov_b64 s[12:13], 0
	v_readlane_b32 s15, v253, 55
	v_readlane_b32 s16, v253, 56
	v_readlane_b32 s17, v253, 57
	v_readlane_b32 s18, v253, 58
	v_readlane_b32 s19, v253, 59
	v_readlane_b32 s20, v253, 60
	v_readlane_b32 s21, v253, 61
	v_readlane_b32 s22, v253, 62
	v_readlane_b32 s23, v253, 63
	v_readlane_b32 s24, v252, 0
	v_readlane_b32 s25, v252, 1
	global_load_dwordx4 v[56:59], v[34:35], off
	global_load_dwordx4 v[60:63], v[34:35], off offset:1024
	global_load_dwordx4 v[64:67], v[34:35], off offset:2048
	global_load_dwordx4 v[68:71], v[34:35], off offset:3072
	global_load_dwordx4 v[72:75], v[36:37], off
	global_load_dwordx4 v[76:79], v[36:37], off offset:1024
	global_load_dwordx4 v[80:83], v[36:37], off offset:2048
	global_load_dwordx4 v[84:87], v[36:37], off offset:3072
	s_branch .LBB0_614
.Lmy_p0_noln:
	s_cmp_eq_u64 s[92:93], 0
	s_cbranch_scc1 .Lmy_p0_w0
	s_waitcnt vmcnt(4)
	s_branch .LBB0_613

;     ...
;       for (int i = 0; i < 4; ++i) { v[i].x -= mean; v[i].y -= mean; v[i].z -= mean; v[i].w -= mean; q += v[i].x * v[i].x + v[i].y * v[i].y + v[i].z * v[i].z + v[i].w * v[i].w; }
;       const float rstd = rsqrtf(wave_sum(q) * (1.f / 1024.f) + 1e-5f);
;       if (mode != 2 && lane == 0) *(float2*)(P.stats + (size_t)m * 2) = make_float2(mean, rstd);
; #pragma unroll
;       for (int i = 0; i < 4; ++i) {
;         float4 g4 = *(const float4*)(lg + i * 256 + lane * 4), b4 = *(const float4*)(lb + i * 256 + lane * 4);
;         v[i].x = v[i].x * rstd * g4.x + b4.x; v[i].y = v[i].y * rstd * g4.y + b4.y; v[i].z = v[i].z * rstd * g4.z + b4.z; v[i].w = v[i].w * rstd * g4.w + b4.w;
;       }
.LBB0_612:
	s_or_b64 exec, exec, s[6:7]
	v_pk_mul_f32 v[8:9], v[8:9], v[42:43] op_sel_hi:[1,0]
	v_pk_mul_f32 v[10:11], v[10:11], v[42:43] op_sel_hi:[1,0]
	v_pk_mul_f32 v[12:13], v[12:13], v[42:43] op_sel_hi:[1,0]
	v_pk_mul_f32 v[14:15], v[14:15], v[42:43] op_sel_hi:[1,0]
	v_pk_mul_f32 v[4:5], v[4:5], v[42:43] op_sel_hi:[1,0]
	v_pk_mul_f32 v[6:7], v[6:7], v[42:43] op_sel_hi:[1,0]
	v_pk_mul_f32 v[0:1], v[0:1], v[42:43] op_sel_hi:[1,0]
	v_pk_mul_f32 v[2:3], v[2:3], v[42:43] op_sel_hi:[1,0]
	s_cmp_eq_u64 s[92:93], 0
	s_cbranch_scc1 .Lmy_p0_a1
	s_waitcnt vmcnt(5)
	s_branch .Lmy_p0_ad

; DI unsigned pack2(float a, float b) { f32v2 v = {a, b}; bf16v2 r = __builtin_convertvector(v, bf16v2); return __builtin_bit_cast(unsigned, r); }
;     ...
;       for (int i = 0; i < 4; ++i) {
;         float4 g4 = *(const float4*)(lg + i * 256 + lane * 4), b4 = *(const float4*)(lb + i * 256 + lane * 4);
;         v[i].x = v[i].x * rstd * g4.x + b4.x; v[i].y = v[i].y * rstd * g4.y + b4.y; v[i].z = v[i].z * rstd * g4.z + b4.z; v[i].w = v[i].w * rstd * g4.w + b4.w;
;       }
;     }
;     if (dummy) {
; #pragma unroll
;       for (int i = 0; i < 4; ++i) { asm volatile("" :: "v"(v[i].x), "v"(v[i].y), "v"(v[i].z), "v"(v[i].w)); v[i] = v0s[i]; }
;     }
;     if (mode == 2 || dummy) {
; #pragma unroll
;       for (int i = 0; i < 4; ++i) *(float4*)(xr + i * 256 + lane * 4) = v[i];
;     }
;     if (mode != 2) {
;       const int modrow = isctx ? 16 : b;
;       const float* md = P.mod + ((size_t)(l * 17 + modrow)) * 6144;
; #pragma unroll
;       for (int i = 0; i < 4; ++i) {
;         float4 sh = *(const float4*)(md + shofs + i * 256 + lane * 4), sc = *(const float4*)(md + scofs + i * 256 + lane * 4);
;         uint2 o;
;         o.x = pack2(v[i].x * (1.f + sc.x) + sh.x, v[i].y * (1.f + sc.y) + sh.y);
;         o.y = pack2(v[i].z * (1.f + sc.z) + sh.z, v[i].w * (1.f + sc.w) + sh.w);
;         *(uint2*)(P.abuf + (size_t)m * D + i * 256 + lane * 4) = o;
;       }
.Lmy_p0_ad:
	v_pk_fma_f32 v[8:9], v[8:9], v[56:57], v[72:73]
	v_pk_fma_f32 v[10:11], v[10:11], v[58:59], v[74:75]
	v_pk_fma_f32 v[12:13], v[12:13], v[60:61], v[76:77]
	v_pk_fma_f32 v[14:15], v[14:15], v[62:63], v[78:79]
	v_pk_fma_f32 v[4:5], v[4:5], v[64:65], v[80:81]
	v_pk_fma_f32 v[6:7], v[6:7], v[66:67], v[82:83]
	v_pk_fma_f32 v[0:1], v[0:1], v[68:69], v[84:85]
	v_pk_fma_f32 v[2:3], v[2:3], v[70:71], v[86:87]
.LBB0_613:
	v_readlane_b32 s6, v251, 27
	v_readlane_b32 s7, v251, 28
	v_mov_b32_e32 v33, v43
	v_readlane_b32 s16, v253, 20
	v_readlane_b32 s20, v253, 24
	v_readlane_b32 s21, v253, 25
	v_readlane_b32 s17, v253, 21
	v_readlane_b32 s18, v253, 22
	v_readlane_b32 s19, v253, 23
	v_readlane_b32 s22, v253, 26
	v_readlane_b32 s23, v253, 27
	v_readlane_b32 s24, v253, 28
	v_readlane_b32 s25, v253, 29
	v_readlane_b32 s26, v253, 30
	v_readlane_b32 s27, v253, 31
	v_readlane_b32 s28, v253, 32
	v_readlane_b32 s29, v253, 33
	v_readlane_b32 s30, v253, 34
	v_readlane_b32 s31, v253, 35
	v_lshl_add_u64 v[38:39], v[38:39], 0, s[6:7]
	v_readlane_b32 s6, v251, 31
	v_readlane_b32 s7, v251, 32
	v_pk_add_f32 v[114:115], v[114:115], 1.0 op_sel_hi:[1,0]
	v_pk_add_f32 v[116:117], v[116:117], 1.0 op_sel_hi:[1,0]
	v_pk_add_f32 v[118:119], v[118:119], 1.0 op_sel_hi:[1,0]
	v_pk_add_f32 v[120:121], v[120:121], 1.0 op_sel_hi:[1,0]
	v_pk_add_f32 v[122:123], v[122:123], 1.0 op_sel_hi:[1,0]
	v_pk_add_f32 v[124:125], v[124:125], 1.0 op_sel_hi:[1,0]
	v_pk_add_f32 v[126:127], v[126:127], 1.0 op_sel_hi:[1,0]
	v_pk_add_f32 v[128:129], v[128:129], 1.0 op_sel_hi:[1,0]
	v_pk_fma_f32 v[8:9], v[8:9], v[114:115], v[98:99]
	v_pk_fma_f32 v[10:11], v[10:11], v[116:117], v[100:101]
	v_pk_fma_f32 v[12:13], v[12:13], v[118:119], v[102:103]
	v_pk_fma_f32 v[14:15], v[14:15], v[120:121], v[104:105]
	v_pk_fma_f32 v[4:5], v[4:5], v[122:123], v[106:107]
	v_pk_fma_f32 v[6:7], v[6:7], v[124:125], v[108:109]
	v_pk_fma_f32 v[0:1], v[0:1], v[126:127], v[110:111]
	v_pk_fma_f32 v[2:3], v[2:3], v[128:129], v[112:113]
	v_cvt_pk_bf16_f32 v8, v8, v9
	v_cvt_pk_bf16_f32 v9, v10, v11
	v_cvt_pk_bf16_f32 v12, v12, v13
	v_cvt_pk_bf16_f32 v13, v14, v15
	v_cvt_pk_bf16_f32 v4, v4, v5
	v_cvt_pk_bf16_f32 v5, v6, v7
	v_cvt_pk_bf16_f32 v0, v0, v1
	v_cvt_pk_bf16_f32 v1, v2, v3
	global_store_dwordx2 v[40:41], v[8:9], off
	global_store_dwordx2 v[40:41], v[12:13], off offset:512
	global_store_dwordx2 v[40:41], v[4:5], off offset:1024
	global_store_dwordx2 v[40:41], v[0:1], off offset:1536
	s_waitcnt vmcnt(4)
	v_mov_b32_e32 v8, v16
	v_mov_b32_e32 v9, v17
	v_mov_b32_e32 v10, v18
	v_mov_b32_e32 v11, v19
	v_mov_b32_e32 v12, v20
	v_mov_b32_e32 v13, v21
	v_mov_b32_e32 v14, v22
	v_mov_b32_e32 v15, v23
	v_mov_b32_e32 v4, v24
	v_mov_b32_e32 v5, v25
	v_mov_b32_e32 v6, v26
	v_mov_b32_e32 v7, v27
	v_mov_b32_e32 v0, v28
	v_mov_b32_e32 v1, v29
	v_mov_b32_e32 v2, v30
	v_mov_b32_e32 v3, v31
	v_lshl_add_u64 v[40:41], v[40:41], 0, s[6:7]
	s_andn2_b64 exec, exec, s[12:13]
	s_cbranch_execz .LBB0_631
.LBB0_614:
	v_readlane_b32 s6, v251, 29
	v_readlane_b32 s7, v251, 30
	s_waitcnt vmcnt(4)
	v_mov_b32_e32 v19, v11
	v_add_u32_e32 v43, s6, v33
	s_mov_b32 s6, 0x9000
	v_cmp_gt_i32_e32 vcc, s6, v43
	s_mov_b32 s6, 0x8fff
	v_cmp_lt_i32_e64 s[6:7], s6, v43
	v_mov_b32_e32 v18, v10
	v_mov_b32_e32 v17, v9
	v_mov_b32_e32 v16, v8
	v_mov_b32_e32 v23, v15
	v_mov_b32_e32 v22, v14
	v_mov_b32_e32 v21, v13
	v_mov_b32_e32 v20, v12
	v_mov_b32_e32 v27, v7
	v_mov_b32_e32 v26, v6
	v_mov_b32_e32 v25, v5
	v_mov_b32_e32 v24, v4
	v_mov_b32_e32 v31, v3
	v_mov_b32_e32 v30, v2
	v_mov_b32_e32 v29, v1
	v_mov_b32_e32 v28, v0
	s_mov_b32 s88, 0x38e38e39
	v_mul_hi_i32 v88, v33, s88
	v_lshrrev_b32_e32 v89, 31, v88
	v_ashrrev_i32_e32 v88, 9, v88
	v_add_u32_e32 v88, v88, v89
	s_movk_i32 s88, 0xf700
	v_mad_i32_i24 v89, v88, s88, v33
	v_cmp_lt_i32_e64 s[90:91], s94, v89
	v_readlane_b32 s78, v253, 24
	v_readlane_b32 s79, v253, 25
	s_movk_i32 s88, 0x6000
	v_cndmask_b32_e64 v88, 16, v88, s[90:91]
	v_add_u32_e32 v88, s14, v88
	v_mov_b64_e32 v[90:91], s[78:79]
	v_mad_i64_i32 v[90:91], s[92:93], v88, s88, v[90:91]
	v_lshlrev_b32_e32 v96, 2, v32
	v_lshl_add_u64 v[90:91], v[90:91], 0, v[96:97]
	s_mov_b64 s[78:79], 0x1000
	v_lshl_add_u64 v[92:93], v[90:91], 0, s[78:79]
	global_load_dwordx4 v[98:101], v[90:91], off
	global_load_dwordx4 v[102:105], v[90:91], off offset:1024
	global_load_dwordx4 v[106:109], v[90:91], off offset:2048
	global_load_dwordx4 v[110:113], v[90:91], off offset:3072
	global_load_dwordx4 v[114:117], v[92:93], off
	global_load_dwordx4 v[118:121], v[92:93], off offset:1024
	global_load_dwordx4 v[122:125], v[92:93], off offset:2048
	global_load_dwordx4 v[126:129], v[92:93], off offset:3072
	s_and_saveexec_b64 s[34:35], vcc
	s_mov_b64 s[92:93], exec
	s_cbranch_execz .LBB0_628
	s_mov_b32 s8, 0x38e38e39
	v_mul_hi_i32 v16, v43, s8
	v_lshrrev_b32_e32 v17, 31, v16
	v_ashrrev_i32_e32 v16, 9, v16
	v_add_u32_e32 v17, v16, v17
	s_movk_i32 s8, 0xf700
	v_mul_i32_i24_e32 v21, 0xfffff700, v17
	v_mad_i32_i24 v20, v17, s8, v43
	v_readlane_b32 s8, v251, 29
	v_readlane_b32 s9, v251, 30
	s_and_b64 vcc, exec, s[0:1]
	v_add3_u32 v16, s8, v21, v33
	v_cmp_lt_i32_e64 s[8:9], s94, v16
	s_mov_b64 s[76:77], -1
	s_cbranch_vccnz .LBB0_621
	v_mov_b64_e32 v[18:19], s[62:63]
	s_and_saveexec_b64 s[16:17], s[8:9]
	s_xor_b64 s[76:77], exec, s[16:17]
	s_cbranch_execz .LBB0_618
	v_readlane_b32 s16, v253, 0
	v_lshlrev_b32_e32 v16, 11, v17
	s_movk_i32 s15, 0xff00
	v_readlane_b32 s26, v253, 10
	v_readlane_b32 s27, v253, 11
	v_add3_u32 v16, v16, v20, s15
	v_readlane_b32 s17, v253, 1
	v_readlane_b32 s18, v253, 2
	v_readlane_b32 s19, v253, 3
	v_readlane_b32 s20, v253, 4
	v_readlane_b32 s21, v253, 5
	v_readlane_b32 s22, v253, 6
	v_readlane_b32 s23, v253, 7
	v_readlane_b32 s24, v253, 8
	v_readlane_b32 s25, v253, 9
	v_readlane_b32 s28, v253, 12
	v_readlane_b32 s29, v253, 13
	v_readlane_b32 s30, v253, 14
	v_readlane_b32 s31, v253, 15
	v_mov_b64_e32 v[18:19], s[26:27]
